# flash loops: K/V LDS-DMA issue moved from after the tile barrier to the end of the iteration (off the barrier->QK critical path)
# speedup vs baseline: 1.0066x; 1.0048x over previous
;     ...
;     if (t + NST - 1 < ntile) {
;       const int sn = (stage == 0) ? NST - 1 : stage - 1;
;       FA_ISSUE(t + NST - 1, sn)
;     }
;     const int kb = kb0 + t;
;     if (fa_active<DK, DV, MODE>(kb, wave_qmax, sel)) {
;       f32x16 S[2];
;       const char* base = smem + stage * C::STAGE;
;       fa_qk<DK, DV, MODE>(S, q, base, lr, lh);
;       fa_softmax_pv<DK, DV, MODE>(S, m, l, O, scale, base, kb, qpos, wave_qmax, sel, lr, lh, variant);
;     }
;     stage = (stage == NST - 1) ? 0 : stage + 1;
.LBB0_363:
	s_or_b64 exec, exec, s[10:11]
	s_cmp_ge_u32 s16, s19
	s_cbranch_scc1 .Ldma_skip_mla1
	s_add_i32 s98, s6, 0xffffa800
	s_cmp_lg_u32 s22, 0
	s_cselect_b32 s98, s98, 0x10800
	s_add_i32 s98, s98, 0
	v_add_u32_e32 v247, s98, v107
	s_nop 0
	v_readfirstlane_b32 s99, v247
	v_add_u32_e32 v247, s98, v93
	s_mov_b32 m0, s99
	v_readfirstlane_b32 s99, v247
	v_add_u32_e32 v247, s98, v108
	global_load_lds_dwordx4 v[102:103], off
	s_mov_b32 m0, s99
	v_readfirstlane_b32 s98, v247
	global_load_lds_dwordx4 v[100:101], off
	s_mov_b32 m0, s98
	s_nop 0
	global_load_lds_dwordx4 v[98:99], off
.Ldma_skip_mla1:
	s_add_i32 s6, s22, 1
	s_cmp_lg_u32 s22, 3
	s_cselect_b32 s22, s6, 0
	s_add_i32 s20, s20, 64
	s_add_i32 s16, s16, 1
	s_add_i32 s21, s21, -1
	v_lshl_add_u64 v[98:99], v[98:99], 0, v[96:97]
	v_lshl_add_u64 v[100:101], v[100:101], 0, v[94:95]
	s_cmp_lg_u32 s18, s20
	v_lshl_add_u64 v[102:103], v[102:103], 0, v[0:1]
	s_cbranch_scc0 .LBB0_378

;     ...
;     raw_barrier();
;     if (t + NST - 1 < ntile) {
;       const int sn = (stage == 0) ? NST - 1 : stage - 1;
;       FA_ISSUE(t + NST - 1, sn)
;     }
;     const int kb = kb0 + t;
;     if (fa_active<DK, DV, MODE>(kb, wave_qmax, sel)) {
;       f32x16 S[2];
;       const char* base = smem + stage * C::STAGE;
.LBB0_372:
	s_waitcnt lgkmcnt(0)
	s_barrier
	s_mul_i32 s6, s22, 0x5800

;     ...
;     if (t + NST - 1 < ntile) {
;       const int sn = (stage == 0) ? NST - 1 : stage - 1;
;       FA_ISSUE(t + NST - 1, sn)
;     }
;     const int kb = kb0 + t;
;     if (fa_active<DK, DV, MODE>(kb, wave_qmax, sel)) {
;       f32x16 S[2];
;       const char* base = smem + stage * C::STAGE;
;       fa_qk<DK, DV, MODE>(S, q, base, lr, lh);
;       fa_softmax_pv<DK, DV, MODE>(S, m, l, O, scale, base, kb, qpos, wave_qmax, sel, lr, lh, variant);
;     }
;     stage = (stage == NST - 1) ? 0 : stage + 1;
.LBB0_425:
	s_add_i32 s98, s0, 3
	s_cmp_gt_u32 s98, s46
	s_cbranch_scc1 .Ldma_skip_sel1
	s_add_i32 s98, s6, 0xffffb800
	s_cmp_lg_u32 s48, 0
	s_cselect_b32 s98, s98, 0xd800
	s_add_i32 s98, s98, 0
	v_add_u32_e32 v247, s98, v112
	s_nop 0
	v_readfirstlane_b32 s99, v247
	v_add_u32_e32 v247, s98, v111
	s_mov_b32 m0, s99
	v_readfirstlane_b32 s99, v247
	v_add_u32_e32 v247, s98, v113
	global_load_lds_dwordx4 v[108:109], off
	s_mov_b32 m0, s99
	v_readfirstlane_b32 s98, v247
	global_load_lds_dwordx4 v[106:107], off
	s_mov_b32 m0, s98
	s_nop 0
	global_load_lds_dwordx4 v[104:105], off

;     ...
;     raw_barrier();
;     if (t + NST - 1 < ntile) {
;       const int sn = (stage == 0) ? NST - 1 : stage - 1;
;       FA_ISSUE(t + NST - 1, sn)
;     }
;     const int kb = kb0 + t;
;     if (fa_active<DK, DV, MODE>(kb, wave_qmax, sel)) {
;       f32x16 S[2];
;       const char* base = smem + stage * C::STAGE;
.LBB0_434:
	s_waitcnt lgkmcnt(0)
	s_barrier
	s_mul_i32 s6, s48, 0x4800

;     ...
;     if (t + NST - 1 < ntile) {
;       const int sn = (stage == 0) ? NST - 1 : stage - 1;
;       FA_ISSUE(t + NST - 1, sn)
;     }
;     const int kb = kb0 + t;
;     if (fa_active<DK, DV, MODE>(kb, wave_qmax, sel)) {
;       f32x16 S[2];
;       const char* base = smem + stage * C::STAGE;
;       fa_qk<DK, DV, MODE>(S, q, base, lr, lh);
;       fa_softmax_pv<DK, DV, MODE>(S, m, l, O, scale, base, kb, qpos, wave_qmax, sel, lr, lh, variant);
;     }
;     stage = (stage == NST - 1) ? 0 : stage + 1;
.LBB0_456:
	s_cmp_gt_u32 s19, 5
	s_cbranch_scc1 .Ldma_skip_win1
	s_add_i32 s98, s0, 0xffffb800
	s_cmp_lg_u32 s21, 0
	s_cselect_b32 s98, s98, 0xd800
	s_add_i32 s98, s98, 0
	v_add_u32_e32 v247, s98, v170
	s_nop 0
	v_readfirstlane_b32 s99, v247
	v_add_u32_e32 v247, s98, v169
	s_mov_b32 m0, s99
	v_readfirstlane_b32 s99, v247
	v_add_u32_e32 v247, s98, v171
	global_load_lds_dwordx4 v[160:161], off
	s_mov_b32 m0, s99
	v_readfirstlane_b32 s98, v247
	global_load_lds_dwordx4 v[158:159], off
	s_mov_b32 m0, s98
	s_nop 0
	global_load_lds_dwordx4 v[156:157], off

;     ...
;     raw_barrier();
;     if (t + NST - 1 < ntile) {
;       const int sn = (stage == 0) ? NST - 1 : stage - 1;
;       FA_ISSUE(t + NST - 1, sn)
;     }
;     const int kb = kb0 + t;
;     if (fa_active<DK, DV, MODE>(kb, wave_qmax, sel)) {
;       f32x16 S[2];
;       const char* base = smem + stage * C::STAGE;
.LBB0_465:
	s_waitcnt lgkmcnt(0)
	s_barrier
	s_mul_i32 s0, s21, 0x4800

;     ...
;     if (t + NST - 1 < ntile) {
;       const int sn = (stage == 0) ? NST - 1 : stage - 1;
;       FA_ISSUE(t + NST - 1, sn)
;     }
;     const int kb = kb0 + t;
;     if (fa_active<DK, DV, MODE>(kb, wave_qmax, sel)) {
;       f32x16 S[2];
;       const char* base = smem + stage * C::STAGE;
;       fa_qk<DK, DV, MODE>(S, q, base, lr, lh);
;       fa_softmax_pv<DK, DV, MODE>(S, m, l, O, scale, base, kb, qpos, wave_qmax, sel, lr, lh, variant);
;     }
;     stage = (stage == NST - 1) ? 0 : stage + 1;
.LBB0_488:
	s_or_b64 exec, exec, s[10:11]
	s_cmp_ge_u32 s17, s18
	s_cbranch_scc1 .Ldma_skip_mla2
	s_add_i32 s98, s6, 0xffffa800
	s_cmp_lg_u32 s44, 0
	s_cselect_b32 s98, s98, 0x10800
	s_add_i32 s98, s98, 0
	v_add_u32_e32 v247, s98, v107
	s_nop 0
	v_readfirstlane_b32 s99, v247
	v_add_u32_e32 v247, s98, v93
	s_mov_b32 m0, s99
	v_readfirstlane_b32 s99, v247
	v_add_u32_e32 v247, s98, v108
	global_load_lds_dwordx4 v[102:103], off
	s_mov_b32 m0, s99
	v_readfirstlane_b32 s98, v247
	global_load_lds_dwordx4 v[100:101], off
	s_mov_b32 m0, s98
	s_nop 0
	global_load_lds_dwordx4 v[98:99], off
.Ldma_skip_mla2:
	s_add_i32 s6, s44, 1
	s_cmp_lg_u32 s44, 3
	s_cselect_b32 s44, s6, 0
	s_add_i32 s21, s21, 64
	s_add_i32 s17, s17, 1
	s_add_i32 s43, s43, -1
	v_lshl_add_u64 v[98:99], v[98:99], 0, v[96:97]
	v_lshl_add_u64 v[100:101], v[100:101], 0, v[94:95]
	s_cmp_lg_u32 s20, s21
	v_lshl_add_u64 v[102:103], v[102:103], 0, v[0:1]
	s_cbranch_scc0 .LBB0_503

;     ...
;     raw_barrier();
;     if (t + NST - 1 < ntile) {
;       const int sn = (stage == 0) ? NST - 1 : stage - 1;
;       FA_ISSUE(t + NST - 1, sn)
;     }
;     const int kb = kb0 + t;
;     if (fa_active<DK, DV, MODE>(kb, wave_qmax, sel)) {
;       f32x16 S[2];
;       const char* base = smem + stage * C::STAGE;
.LBB0_497:
	s_waitcnt lgkmcnt(0)
	s_barrier
	s_mul_i32 s6, s44, 0x5800

;     ...
;     if (t + NST - 1 < ntile) {
;       const int sn = (stage == 0) ? NST - 1 : stage - 1;
;       FA_ISSUE(t + NST - 1, sn)
;     }
;     const int kb = kb0 + t;
;     if (fa_active<DK, DV, MODE>(kb, wave_qmax, sel)) {
;       f32x16 S[2];
;       const char* base = smem + stage * C::STAGE;
;       fa_qk<DK, DV, MODE>(S, q, base, lr, lh);
;       fa_softmax_pv<DK, DV, MODE>(S, m, l, O, scale, base, kb, qpos, wave_qmax, sel, lr, lh, variant);
;     }
;     stage = (stage == NST - 1) ? 0 : stage + 1;
.LBB0_550:
	s_add_i32 s98, s0, 3
	s_cmp_gt_u32 s98, s41
	s_cbranch_scc1 .Ldma_skip_sel2
	s_add_i32 s98, s6, 0xffffb800
	s_cmp_lg_u32 s45, 0
	s_cselect_b32 s98, s98, 0xd800
	s_add_i32 s98, s98, 0
	v_add_u32_e32 v247, s98, v112
	s_nop 0
	v_readfirstlane_b32 s99, v247
	v_add_u32_e32 v247, s98, v15
	s_mov_b32 m0, s99
	v_readfirstlane_b32 s99, v247
	v_add_u32_e32 v247, s98, v113
	global_load_lds_dwordx4 v[12:13], off
	s_mov_b32 m0, s99
	v_readfirstlane_b32 s98, v247
	global_load_lds_dwordx4 v[10:11], off
	s_mov_b32 m0, s98
	s_nop 0
	global_load_lds_dwordx4 v[8:9], off

;     ...
;     raw_barrier();
;     if (t + NST - 1 < ntile) {
;       const int sn = (stage == 0) ? NST - 1 : stage - 1;
;       FA_ISSUE(t + NST - 1, sn)
;     }
;     const int kb = kb0 + t;
;     if (fa_active<DK, DV, MODE>(kb, wave_qmax, sel)) {
;       f32x16 S[2];
;       const char* base = smem + stage * C::STAGE;
.LBB0_559:
	s_waitcnt lgkmcnt(0)
	s_barrier
	s_mul_i32 s6, s45, 0x4800

;     ...
;     if (t + NST - 1 < ntile) {
;       const int sn = (stage == 0) ? NST - 1 : stage - 1;
;       FA_ISSUE(t + NST - 1, sn)
;     }
;     const int kb = kb0 + t;
;     if (fa_active<DK, DV, MODE>(kb, wave_qmax, sel)) {
;       f32x16 S[2];
;       const char* base = smem + stage * C::STAGE;
;       fa_qk<DK, DV, MODE>(S, q, base, lr, lh);
;       fa_softmax_pv<DK, DV, MODE>(S, m, l, O, scale, base, kb, qpos, wave_qmax, sel, lr, lh, variant);
;     }
;     stage = (stage == NST - 1) ? 0 : stage + 1;
.LBB0_586:
	s_cmp_ge_i32 s21, s16
	s_cbranch_scc1 .Ldma_skip_win2
	s_add_i32 s98, s0, 0xffffb800
	s_cmp_lg_u32 s22, 0
	s_cselect_b32 s98, s98, 0xd800
	s_add_i32 s98, s98, 0
	v_add_u32_e32 v247, s98, v15
	s_nop 0
	v_readfirstlane_b32 s99, v247
	v_add_u32_e32 v247, s98, v13
	s_mov_b32 m0, s99
	v_readfirstlane_b32 s99, v247
	v_add_u32_e32 v247, s98, v169
	global_load_lds_dwordx4 v[10:11], off
	s_mov_b32 m0, s99
	v_readfirstlane_b32 s98, v247
	global_load_lds_dwordx4 v[8:9], off
	s_mov_b32 m0, s98
	s_nop 0
	global_load_lds_dwordx4 v[6:7], off

;     ...
;     raw_barrier();
;     if (t + NST - 1 < ntile) {
;       const int sn = (stage == 0) ? NST - 1 : stage - 1;
;       FA_ISSUE(t + NST - 1, sn)
;     }
;     const int kb = kb0 + t;
;     if (fa_active<DK, DV, MODE>(kb, wave_qmax, sel)) {
;       f32x16 S[2];
;       const char* base = smem + stage * C::STAGE;
.LBB0_595:
	s_waitcnt lgkmcnt(0)
	s_barrier
	s_mul_i32 s0, s22, 0x4800
